# P3 gate epilogue: second half's gate loads issued early into free VGPRs, counted waits re-derived
# speedup vs baseline: 1.0038x; 1.0038x over previous
; __device__ __forceinline__ float clampg(unsigned bits) { return __uint_as_float(bits > 0x0da24260u ? bits : 0x0da24260u); }
;     __device__ __forceinline__ void operator()(acc_t& acc, const Unit& u, int wr, int wc, int fr, int fq) const {
;     ...
;         for (int ai = 0; ai < 2; ++ai) {
;             u32x4 ga[4][2], gb[4][2];
; #pragma unroll
;             for (int m = 0; m < 4; ++m)
; #pragma unroll
;                 for (int bj = 0; bj < 2; ++bj) { const size_t o = (size_t)(ai * HALF + m * 16) * D + HALF * bj; ga[m][bj] = *(const u32x4*)(Ga + o); if (br < 2) gb[m][bj] = *(const u32x4*)(Gb + o); }
; #pragma unroll
;             for (int m = 0; m < 4; ++m)
; #pragma unroll
;                 for (int bj = 0; bj < 2; ++bj) {
;                     const u32x4 a = ga[m][bj]; float f[8] = {clampg(a.x << 16), clampg(a.x & 0xffff0000u), clampg(a.y << 16), clampg(a.y & 0xffff0000u), clampg(a.z << 16), clampg(a.z & 0xffff0000u), clampg(a.w << 16), clampg(a.w & 0xffff0000u)};
;                     if (br < 2) { const u32x4 b = gb[m][bj]; const float d[8] = {clampg(b.x << 16), clampg(b.x & 0xffff0000u), clampg(b.y << 16), clampg(b.y & 0xffff0000u), clampg(b.z << 16), clampg(b.z & 0xffff0000u), clampg(b.w << 16), clampg(b.w & 0xffff0000u)};
.LBB0_597:
	v_add_co_u32_e32 v244, vcc, 0x40000, v200
	s_nop 1
	v_addc_co_u32_e32 v245, vcc, 0, v201, vcc
	global_load_dwordx4 v[220:223], v[244:245], off nt
	v_add_co_u32_e32 v244, vcc, 0x40000, v200
	s_nop 1
	v_addc_co_u32_e32 v245, vcc, 0, v201, vcc
	global_load_dwordx4 v[224:227], v[244:245], off offset:256 nt
	v_add_co_u32_e32 v244, vcc, 0x48000, v200
	s_nop 1
	v_addc_co_u32_e32 v245, vcc, 0, v201, vcc
	global_load_dwordx4 v[228:231], v[244:245], off nt
	v_add_co_u32_e32 v244, vcc, 0x48000, v200
	s_nop 1
	v_addc_co_u32_e32 v245, vcc, 0, v201, vcc
	global_load_dwordx4 v[232:235], v[244:245], off offset:256 nt
	v_add_co_u32_e32 v244, vcc, 0x50000, v200
	s_nop 1
	v_addc_co_u32_e32 v245, vcc, 0, v201, vcc
	global_load_dwordx4 v[236:239], v[244:245], off nt
	v_add_co_u32_e32 v244, vcc, 0x50000, v200
	s_nop 1
	v_addc_co_u32_e32 v245, vcc, 0, v201, vcc
	global_load_dwordx4 v[240:243], v[244:245], off offset:256 nt
	s_waitcnt vmcnt(12)
	v_lshlrev_b32_e32 v202, 16, v190
	v_and_b32_e32 v190, 0xffff0000, v190
	v_max_u32_e32 v205, 0xda24260, v190
	v_lshlrev_b32_e32 v190, 16, v191
	v_max_u32_e32 v204, 0xda24260, v202
	v_max_u32_e32 v202, 0xda24260, v190
	v_and_b32_e32 v190, 0xffff0000, v191
	v_max_u32_e32 v203, 0xda24260, v190
	v_lshlrev_b32_e32 v190, 16, v192
	v_max_u32_e32 v206, 0xda24260, v190
	v_and_b32_e32 v190, 0xffff0000, v192
	v_max_u32_e32 v207, 0xda24260, v190
	v_lshlrev_b32_e32 v190, 16, v193
	v_and_b32_e32 v191, 0xffff0000, v193
	v_cndmask_b32_e64 v192, 0, 1, s[2:3]
	v_max_u32_e32 v190, 0xda24260, v190
	v_max_u32_e32 v191, 0xda24260, v191
	v_cmp_ne_u32_e64 s[6:7], 1, v192
	s_andn2_b64 vcc, exec, s[2:3]
	s_mov_b64 s[2:3], -1
	s_cbranch_vccnz .LBB0_599
	s_mov_b64 s[2:3], 0

; __device__ __forceinline__ float clampg(unsigned bits) { return __uint_as_float(bits > 0x0da24260u ? bits : 0x0da24260u); }
;     __device__ __forceinline__ void operator()(acc_t& acc, const Unit& u, int wr, int wc, int fr, int fq) const {
;     ...
;         for (int ai = 0; ai < 2; ++ai) {
;             u32x4 ga[4][2], gb[4][2];
; #pragma unroll
;             for (int m = 0; m < 4; ++m)
; #pragma unroll
;                 for (int bj = 0; bj < 2; ++bj) { const size_t o = (size_t)(ai * HALF + m * 16) * D + HALF * bj; ga[m][bj] = *(const u32x4*)(Ga + o); if (br < 2) gb[m][bj] = *(const u32x4*)(Gb + o); }
; #pragma unroll
;             for (int m = 0; m < 4; ++m)
; #pragma unroll
;                 for (int bj = 0; bj < 2; ++bj) {
;                     const u32x4 a = ga[m][bj]; float f[8] = {clampg(a.x << 16), clampg(a.x & 0xffff0000u), clampg(a.y << 16), clampg(a.y & 0xffff0000u), clampg(a.z << 16), clampg(a.z & 0xffff0000u), clampg(a.w << 16), clampg(a.w & 0xffff0000u)};
;                     if (br < 2) { const u32x4 b = gb[m][bj]; const float d[8] = {clampg(b.x << 16), clampg(b.x & 0xffff0000u), clampg(b.y << 16), clampg(b.y & 0xffff0000u), clampg(b.z << 16), clampg(b.z & 0xffff0000u), clampg(b.w << 16), clampg(b.w & 0xffff0000u)};
.LBB0_604:
	s_and_b64 vcc, exec, s[4:5]
	s_cbranch_vccnz .Lp3g_0
	v_add_co_u32_e32 v244, vcc, 0x40000, v198
	s_nop 1
	v_addc_co_u32_e32 v245, vcc, 0, v199, vcc
	global_load_dwordx4 v[158:161], v[244:245], off
.Lp3g_0:
	s_waitcnt vmcnt(12)
	v_lshlrev_b32_e32 v190, 16, v186
	v_and_b32_e32 v186, 0xffff0000, v186
	v_max_u32_e32 v193, 0xda24260, v186
	v_lshlrev_b32_e32 v186, 16, v187
	v_max_u32_e32 v192, 0xda24260, v190
	v_max_u32_e32 v190, 0xda24260, v186
	v_and_b32_e32 v186, 0xffff0000, v187
	v_max_u32_e32 v191, 0xda24260, v186
	v_lshlrev_b32_e32 v186, 16, v188
	v_max_u32_e32 v202, 0xda24260, v186
	v_and_b32_e32 v186, 0xffff0000, v188
	v_max_u32_e32 v203, 0xda24260, v186
	v_lshlrev_b32_e32 v186, 16, v189
	v_and_b32_e32 v187, 0xffff0000, v189
	v_max_u32_e32 v186, 0xda24260, v186
	v_max_u32_e32 v187, 0xda24260, v187
	s_and_b64 vcc, exec, s[6:7]
	s_mov_b64 s[2:3], -1
	s_cbranch_vccnz .LBB0_606
	s_mov_b64 s[2:3], 0

; __device__ __forceinline__ float clampg(unsigned bits) { return __uint_as_float(bits > 0x0da24260u ? bits : 0x0da24260u); }
;     __device__ __forceinline__ void operator()(acc_t& acc, const Unit& u, int wr, int wc, int fr, int fq) const {
;     ...
;         for (int ai = 0; ai < 2; ++ai) {
;             u32x4 ga[4][2], gb[4][2];
; #pragma unroll
;             for (int m = 0; m < 4; ++m)
; #pragma unroll
;                 for (int bj = 0; bj < 2; ++bj) { const size_t o = (size_t)(ai * HALF + m * 16) * D + HALF * bj; ga[m][bj] = *(const u32x4*)(Ga + o); if (br < 2) gb[m][bj] = *(const u32x4*)(Gb + o); }
; #pragma unroll
;             for (int m = 0; m < 4; ++m)
; #pragma unroll
;                 for (int bj = 0; bj < 2; ++bj) {
;                     const u32x4 a = ga[m][bj]; float f[8] = {clampg(a.x << 16), clampg(a.x & 0xffff0000u), clampg(a.y << 16), clampg(a.y & 0xffff0000u), clampg(a.z << 16), clampg(a.z & 0xffff0000u), clampg(a.w << 16), clampg(a.w & 0xffff0000u)};
;                     if (br < 2) { const u32x4 b = gb[m][bj]; const float d[8] = {clampg(b.x << 16), clampg(b.x & 0xffff0000u), clampg(b.y << 16), clampg(b.y & 0xffff0000u), clampg(b.z << 16), clampg(b.z & 0xffff0000u), clampg(b.w << 16), clampg(b.w & 0xffff0000u)};
.LBB0_611:
	s_and_b64 vcc, exec, s[4:5]
	s_cbranch_vccnz .Lp3g_1
	v_add_co_u32_e32 v244, vcc, 0x40000, v198
	s_nop 1
	v_addc_co_u32_e32 v245, vcc, 0, v199, vcc
	global_load_dwordx4 v[154:157], v[244:245], off offset:256
.Lp3g_1:
	s_waitcnt vmcnt(12)
	v_lshlrev_b32_e32 v186, 16, v182
	v_and_b32_e32 v182, 0xffff0000, v182
	v_max_u32_e32 v189, 0xda24260, v182
	v_lshlrev_b32_e32 v182, 16, v183
	v_max_u32_e32 v188, 0xda24260, v186
	v_max_u32_e32 v186, 0xda24260, v182
	v_and_b32_e32 v182, 0xffff0000, v183
	v_max_u32_e32 v187, 0xda24260, v182
	v_lshlrev_b32_e32 v182, 16, v184
	v_max_u32_e32 v190, 0xda24260, v182
	v_and_b32_e32 v182, 0xffff0000, v184
	v_max_u32_e32 v191, 0xda24260, v182
	v_lshlrev_b32_e32 v182, 16, v185
	v_and_b32_e32 v183, 0xffff0000, v185
	v_max_u32_e32 v182, 0xda24260, v182
	v_max_u32_e32 v183, 0xda24260, v183
	s_and_b64 vcc, exec, s[6:7]
	s_mov_b64 s[2:3], -1
	s_cbranch_vccnz .LBB0_613
	s_mov_b64 s[2:3], 0

; __device__ __forceinline__ float clampg(unsigned bits) { return __uint_as_float(bits > 0x0da24260u ? bits : 0x0da24260u); }
;     __device__ __forceinline__ void operator()(acc_t& acc, const Unit& u, int wr, int wc, int fr, int fq) const {
;     ...
;         for (int ai = 0; ai < 2; ++ai) {
;             u32x4 ga[4][2], gb[4][2];
; #pragma unroll
;             for (int m = 0; m < 4; ++m)
; #pragma unroll
;                 for (int bj = 0; bj < 2; ++bj) { const size_t o = (size_t)(ai * HALF + m * 16) * D + HALF * bj; ga[m][bj] = *(const u32x4*)(Ga + o); if (br < 2) gb[m][bj] = *(const u32x4*)(Gb + o); }
; #pragma unroll
;             for (int m = 0; m < 4; ++m)
; #pragma unroll
;                 for (int bj = 0; bj < 2; ++bj) {
;                     const u32x4 a = ga[m][bj]; float f[8] = {clampg(a.x << 16), clampg(a.x & 0xffff0000u), clampg(a.y << 16), clampg(a.y & 0xffff0000u), clampg(a.z << 16), clampg(a.z & 0xffff0000u), clampg(a.w << 16), clampg(a.w & 0xffff0000u)};
;                     if (br < 2) { const u32x4 b = gb[m][bj]; const float d[8] = {clampg(b.x << 16), clampg(b.x & 0xffff0000u), clampg(b.y << 16), clampg(b.y & 0xffff0000u), clampg(b.z << 16), clampg(b.z & 0xffff0000u), clampg(b.w << 16), clampg(b.w & 0xffff0000u)};
.LBB0_618:
	s_and_b64 vcc, exec, s[4:5]
	s_cbranch_vccnz .Lp3g_2
	v_add_co_u32_e32 v244, vcc, 0x48000, v198
	s_nop 1
	v_addc_co_u32_e32 v245, vcc, 0, v199, vcc
	global_load_dwordx4 v[150:153], v[244:245], off
.Lp3g_2:
	s_waitcnt vmcnt(12)
	v_lshlrev_b32_e32 v182, 16, v178
	v_and_b32_e32 v178, 0xffff0000, v178
	v_max_u32_e32 v185, 0xda24260, v178
	v_lshlrev_b32_e32 v178, 16, v179
	v_max_u32_e32 v184, 0xda24260, v182
	v_max_u32_e32 v182, 0xda24260, v178
	v_and_b32_e32 v178, 0xffff0000, v179
	v_max_u32_e32 v183, 0xda24260, v178
	v_lshlrev_b32_e32 v178, 16, v180
	v_max_u32_e32 v186, 0xda24260, v178
	v_and_b32_e32 v178, 0xffff0000, v180
	v_max_u32_e32 v187, 0xda24260, v178
	v_lshlrev_b32_e32 v178, 16, v181
	v_and_b32_e32 v179, 0xffff0000, v181
	v_max_u32_e32 v178, 0xda24260, v178
	v_max_u32_e32 v179, 0xda24260, v179
	s_and_b64 vcc, exec, s[6:7]
	s_mov_b64 s[2:3], -1
	s_cbranch_vccnz .LBB0_620
	s_mov_b64 s[2:3], 0

; __device__ __forceinline__ float clampg(unsigned bits) { return __uint_as_float(bits > 0x0da24260u ? bits : 0x0da24260u); }
;     __device__ __forceinline__ void operator()(acc_t& acc, const Unit& u, int wr, int wc, int fr, int fq) const {
;     ...
;         for (int ai = 0; ai < 2; ++ai) {
;             u32x4 ga[4][2], gb[4][2];
; #pragma unroll
;             for (int m = 0; m < 4; ++m)
; #pragma unroll
;                 for (int bj = 0; bj < 2; ++bj) { const size_t o = (size_t)(ai * HALF + m * 16) * D + HALF * bj; ga[m][bj] = *(const u32x4*)(Ga + o); if (br < 2) gb[m][bj] = *(const u32x4*)(Gb + o); }
; #pragma unroll
;             for (int m = 0; m < 4; ++m)
; #pragma unroll
;                 for (int bj = 0; bj < 2; ++bj) {
;                     const u32x4 a = ga[m][bj]; float f[8] = {clampg(a.x << 16), clampg(a.x & 0xffff0000u), clampg(a.y << 16), clampg(a.y & 0xffff0000u), clampg(a.z << 16), clampg(a.z & 0xffff0000u), clampg(a.w << 16), clampg(a.w & 0xffff0000u)};
;                     if (br < 2) { const u32x4 b = gb[m][bj]; const float d[8] = {clampg(b.x << 16), clampg(b.x & 0xffff0000u), clampg(b.y << 16), clampg(b.y & 0xffff0000u), clampg(b.z << 16), clampg(b.z & 0xffff0000u), clampg(b.w << 16), clampg(b.w & 0xffff0000u)};
.LBB0_625:
	s_and_b64 vcc, exec, s[4:5]
	s_cbranch_vccnz .Lp3g_3
	v_add_co_u32_e32 v244, vcc, 0x48000, v198
	s_nop 1
	v_addc_co_u32_e32 v245, vcc, 0, v199, vcc
	global_load_dwordx4 v[146:149], v[244:245], off offset:256
.Lp3g_3:
	s_waitcnt vmcnt(12)
	v_lshlrev_b32_e32 v178, 16, v174
	v_and_b32_e32 v174, 0xffff0000, v174
	v_max_u32_e32 v181, 0xda24260, v174
	v_lshlrev_b32_e32 v174, 16, v175
	v_max_u32_e32 v180, 0xda24260, v178
	v_max_u32_e32 v178, 0xda24260, v174
	v_and_b32_e32 v174, 0xffff0000, v175
	v_max_u32_e32 v179, 0xda24260, v174
	v_lshlrev_b32_e32 v174, 16, v176
	v_max_u32_e32 v182, 0xda24260, v174
	v_and_b32_e32 v174, 0xffff0000, v176
	v_max_u32_e32 v183, 0xda24260, v174
	v_lshlrev_b32_e32 v174, 16, v177
	v_and_b32_e32 v175, 0xffff0000, v177
	v_max_u32_e32 v174, 0xda24260, v174
	v_max_u32_e32 v175, 0xda24260, v175
	s_and_b64 vcc, exec, s[6:7]
	s_mov_b64 s[2:3], -1
	s_cbranch_vccnz .LBB0_627
	s_mov_b64 s[2:3], 0

; __device__ __forceinline__ float clampg(unsigned bits) { return __uint_as_float(bits > 0x0da24260u ? bits : 0x0da24260u); }
;     __device__ __forceinline__ void operator()(acc_t& acc, const Unit& u, int wr, int wc, int fr, int fq) const {
;     ...
;         for (int ai = 0; ai < 2; ++ai) {
;             u32x4 ga[4][2], gb[4][2];
; #pragma unroll
;             for (int m = 0; m < 4; ++m)
; #pragma unroll
;                 for (int bj = 0; bj < 2; ++bj) { const size_t o = (size_t)(ai * HALF + m * 16) * D + HALF * bj; ga[m][bj] = *(const u32x4*)(Ga + o); if (br < 2) gb[m][bj] = *(const u32x4*)(Gb + o); }
; #pragma unroll
;             for (int m = 0; m < 4; ++m)
; #pragma unroll
;                 for (int bj = 0; bj < 2; ++bj) {
;                     const u32x4 a = ga[m][bj]; float f[8] = {clampg(a.x << 16), clampg(a.x & 0xffff0000u), clampg(a.y << 16), clampg(a.y & 0xffff0000u), clampg(a.z << 16), clampg(a.z & 0xffff0000u), clampg(a.w << 16), clampg(a.w & 0xffff0000u)};
;                     if (br < 2) { const u32x4 b = gb[m][bj]; const float d[8] = {clampg(b.x << 16), clampg(b.x & 0xffff0000u), clampg(b.y << 16), clampg(b.y & 0xffff0000u), clampg(b.z << 16), clampg(b.z & 0xffff0000u), clampg(b.w << 16), clampg(b.w & 0xffff0000u)};
.LBB0_632:
	s_and_b64 vcc, exec, s[4:5]
	s_cbranch_vccnz .Lp3g_4
	v_add_co_u32_e32 v244, vcc, 0x50000, v198
	s_nop 1
	v_addc_co_u32_e32 v245, vcc, 0, v199, vcc
	global_load_dwordx4 v[142:145], v[244:245], off
.Lp3g_4:
	s_waitcnt vmcnt(12)
	v_lshlrev_b32_e32 v174, 16, v170
	v_and_b32_e32 v170, 0xffff0000, v170
	v_max_u32_e32 v177, 0xda24260, v170
	v_lshlrev_b32_e32 v170, 16, v171
	v_max_u32_e32 v176, 0xda24260, v174
	v_max_u32_e32 v174, 0xda24260, v170
	v_and_b32_e32 v170, 0xffff0000, v171
	v_max_u32_e32 v175, 0xda24260, v170
	v_lshlrev_b32_e32 v170, 16, v172
	v_max_u32_e32 v178, 0xda24260, v170
	v_and_b32_e32 v170, 0xffff0000, v172
	v_max_u32_e32 v179, 0xda24260, v170
	v_lshlrev_b32_e32 v170, 16, v173
	v_and_b32_e32 v171, 0xffff0000, v173
	v_max_u32_e32 v170, 0xda24260, v170
	v_max_u32_e32 v171, 0xda24260, v171
	s_and_b64 vcc, exec, s[6:7]
	s_mov_b64 s[2:3], -1
	s_cbranch_vccnz .LBB0_634
	s_mov_b64 s[2:3], 0

; __device__ __forceinline__ float clampg(unsigned bits) { return __uint_as_float(bits > 0x0da24260u ? bits : 0x0da24260u); }
;     __device__ __forceinline__ void operator()(acc_t& acc, const Unit& u, int wr, int wc, int fr, int fq) const {
;     ...
;         for (int ai = 0; ai < 2; ++ai) {
;             u32x4 ga[4][2], gb[4][2];
; #pragma unroll
;             for (int m = 0; m < 4; ++m)
; #pragma unroll
;                 for (int bj = 0; bj < 2; ++bj) { const size_t o = (size_t)(ai * HALF + m * 16) * D + HALF * bj; ga[m][bj] = *(const u32x4*)(Ga + o); if (br < 2) gb[m][bj] = *(const u32x4*)(Gb + o); }
; #pragma unroll
;             for (int m = 0; m < 4; ++m)
; #pragma unroll
;                 for (int bj = 0; bj < 2; ++bj) {
;                     const u32x4 a = ga[m][bj]; float f[8] = {clampg(a.x << 16), clampg(a.x & 0xffff0000u), clampg(a.y << 16), clampg(a.y & 0xffff0000u), clampg(a.z << 16), clampg(a.z & 0xffff0000u), clampg(a.w << 16), clampg(a.w & 0xffff0000u)};
;                     if (br < 2) { const u32x4 b = gb[m][bj]; const float d[8] = {clampg(b.x << 16), clampg(b.x & 0xffff0000u), clampg(b.y << 16), clampg(b.y & 0xffff0000u), clampg(b.z << 16), clampg(b.z & 0xffff0000u), clampg(b.w << 16), clampg(b.w & 0xffff0000u)};
.LBB0_639:
	s_and_b64 vcc, exec, s[4:5]
	s_cbranch_vccnz .Lp3g_5
	v_add_co_u32_e32 v244, vcc, 0x50000, v198
	s_nop 1
	v_addc_co_u32_e32 v245, vcc, 0, v199, vcc
	global_load_dwordx4 v[138:141], v[244:245], off offset:256
.Lp3g_5:
	s_waitcnt vmcnt(12)
	v_lshlrev_b32_e32 v170, 16, v166
	v_and_b32_e32 v166, 0xffff0000, v166
	v_max_u32_e32 v173, 0xda24260, v166
	v_lshlrev_b32_e32 v166, 16, v167
	v_max_u32_e32 v172, 0xda24260, v170
	v_max_u32_e32 v170, 0xda24260, v166
	v_and_b32_e32 v166, 0xffff0000, v167
	v_max_u32_e32 v171, 0xda24260, v166
	v_lshlrev_b32_e32 v166, 16, v168
	v_max_u32_e32 v174, 0xda24260, v166
	v_and_b32_e32 v166, 0xffff0000, v168
	v_max_u32_e32 v175, 0xda24260, v166
	v_lshlrev_b32_e32 v166, 16, v169
	v_and_b32_e32 v167, 0xffff0000, v169
	v_max_u32_e32 v166, 0xda24260, v166
	v_max_u32_e32 v167, 0xda24260, v167
	s_and_b64 vcc, exec, s[6:7]
	s_mov_b64 s[2:3], -1
	s_cbranch_vccnz .LBB0_641
	s_mov_b64 s[2:3], 0

; __device__ __forceinline__ float clampg(unsigned bits) { return __uint_as_float(bits > 0x0da24260u ? bits : 0x0da24260u); }
;     __device__ __forceinline__ void operator()(acc_t& acc, const Unit& u, int wr, int wc, int fr, int fq) const {
;     ...
;         for (int ai = 0; ai < 2; ++ai) {
;             u32x4 ga[4][2], gb[4][2];
; #pragma unroll
;             for (int m = 0; m < 4; ++m)
; #pragma unroll
;                 for (int bj = 0; bj < 2; ++bj) { const size_t o = (size_t)(ai * HALF + m * 16) * D + HALF * bj; ga[m][bj] = *(const u32x4*)(Ga + o); if (br < 2) gb[m][bj] = *(const u32x4*)(Gb + o); }
; #pragma unroll
;             for (int m = 0; m < 4; ++m)
; #pragma unroll
;                 for (int bj = 0; bj < 2; ++bj) {
;                     const u32x4 a = ga[m][bj]; float f[8] = {clampg(a.x << 16), clampg(a.x & 0xffff0000u), clampg(a.y << 16), clampg(a.y & 0xffff0000u), clampg(a.z << 16), clampg(a.z & 0xffff0000u), clampg(a.w << 16), clampg(a.w & 0xffff0000u)};
;                     if (br < 2) { const u32x4 b = gb[m][bj]; const float d[8] = {clampg(b.x << 16), clampg(b.x & 0xffff0000u), clampg(b.y << 16), clampg(b.y & 0xffff0000u), clampg(b.z << 16), clampg(b.z & 0xffff0000u), clampg(b.w << 16), clampg(b.w & 0xffff0000u)};
.LBB0_646:
	s_waitcnt vmcnt(12)
	v_lshlrev_b32_e32 v166, 16, v162
	v_and_b32_e32 v162, 0xffff0000, v162
	v_max_u32_e32 v169, 0xda24260, v162
	v_lshlrev_b32_e32 v162, 16, v163
	v_max_u32_e32 v168, 0xda24260, v166
	v_max_u32_e32 v166, 0xda24260, v162
	v_and_b32_e32 v162, 0xffff0000, v163
	v_max_u32_e32 v167, 0xda24260, v162
	v_lshlrev_b32_e32 v162, 16, v164
	v_max_u32_e32 v170, 0xda24260, v162
	v_and_b32_e32 v162, 0xffff0000, v164
	v_max_u32_e32 v171, 0xda24260, v162
	v_lshlrev_b32_e32 v162, 16, v165
	v_and_b32_e32 v163, 0xffff0000, v165
	v_max_u32_e32 v162, 0xda24260, v162
	v_max_u32_e32 v163, 0xda24260, v163
	s_and_b64 vcc, exec, s[6:7]
	s_mov_b64 s[2:3], -1
	s_cbranch_vccnz .LBB0_648
	s_mov_b64 s[2:3], 0

; __device__ __forceinline__ float clampg(unsigned bits) { return __uint_as_float(bits > 0x0da24260u ? bits : 0x0da24260u); }
;     __device__ __forceinline__ void operator()(acc_t& acc, const Unit& u, int wr, int wc, int fr, int fq) const {
;     ...
;         for (int ai = 0; ai < 2; ++ai) {
;             u32x4 ga[4][2], gb[4][2];
; #pragma unroll
;             for (int m = 0; m < 4; ++m)
; #pragma unroll
;                 for (int bj = 0; bj < 2; ++bj) { const size_t o = (size_t)(ai * HALF + m * 16) * D + HALF * bj; ga[m][bj] = *(const u32x4*)(Ga + o); if (br < 2) gb[m][bj] = *(const u32x4*)(Gb + o); }
; #pragma unroll
;             for (int m = 0; m < 4; ++m)
; #pragma unroll
;                 for (int bj = 0; bj < 2; ++bj) {
;                     const u32x4 a = ga[m][bj]; float f[8] = {clampg(a.x << 16), clampg(a.x & 0xffff0000u), clampg(a.y << 16), clampg(a.y & 0xffff0000u), clampg(a.z << 16), clampg(a.z & 0xffff0000u), clampg(a.w << 16), clampg(a.w & 0xffff0000u)};
;                     if (br < 2) { const u32x4 b = gb[m][bj]; const float d[8] = {clampg(b.x << 16), clampg(b.x & 0xffff0000u), clampg(b.y << 16), clampg(b.y & 0xffff0000u), clampg(b.z << 16), clampg(b.z & 0xffff0000u), clampg(b.w << 16), clampg(b.w & 0xffff0000u)};
.LBB0_653:
	v_add_co_u32_e32 v244, vcc, 0x58000, v200
	s_nop 1
	v_addc_co_u32_e32 v245, vcc, 0, v201, vcc
	global_load_dwordx4 v[166:169], v[244:245], off nt
	s_and_b64 vcc, exec, s[4:5]
	s_cbranch_vccnz .Lp3t_6
	v_add_co_u32_e32 v244, vcc, 0x58000, v198
	s_nop 1
	v_addc_co_u32_e32 v245, vcc, 0, v199, vcc
	global_load_dwordx4 v[134:137], v[244:245], off
.Lp3t_6:
	v_add_co_u32_e32 v244, vcc, 0x58000, v200
	s_nop 1
	v_addc_co_u32_e32 v245, vcc, 0, v201, vcc
	global_load_dwordx4 v[162:165], v[244:245], off offset:256 nt
	s_and_b64 vcc, exec, s[4:5]
	s_cbranch_vccnz .Lp3t_7
	v_add_co_u32_e32 v244, vcc, 0x58000, v198
	s_nop 1
	v_addc_co_u32_e32 v245, vcc, 0, v199, vcc
	global_load_dwordx4 v[130:133], v[244:245], off offset:256
.Lp3t_7:
.LBB0_669:
	s_waitcnt vmcnt(7)
	v_lshlrev_b32_e32 v198, 16, v220
	v_and_b32_e32 v190, 0xffff0000, v220
	v_max_u32_e32 v201, 0xda24260, v190
	v_lshlrev_b32_e32 v190, 16, v221
	v_max_u32_e32 v200, 0xda24260, v198
	v_max_u32_e32 v198, 0xda24260, v190
	v_and_b32_e32 v190, 0xffff0000, v221
	v_max_u32_e32 v199, 0xda24260, v190
	v_lshlrev_b32_e32 v190, 16, v222
	v_max_u32_e32 v202, 0xda24260, v190
	v_and_b32_e32 v190, 0xffff0000, v222
	v_max_u32_e32 v203, 0xda24260, v190
	v_lshlrev_b32_e32 v190, 16, v223
	v_and_b32_e32 v191, 0xffff0000, v223
	v_max_u32_e32 v190, 0xda24260, v190
	v_max_u32_e32 v191, 0xda24260, v191
	s_and_b64 vcc, exec, s[6:7]
	s_mov_b64 s[2:3], -1
	s_cbranch_vccnz .LBB0_671
	s_mov_b64 s[2:3], 0

; __device__ __forceinline__ float clampg(unsigned bits) { return __uint_as_float(bits > 0x0da24260u ? bits : 0x0da24260u); }
;     __device__ __forceinline__ void operator()(acc_t& acc, const Unit& u, int wr, int wc, int fr, int fq) const {
;     ...
;             for (int m = 0; m < 4; ++m)
; #pragma unroll
;                 for (int bj = 0; bj < 2; ++bj) {
;                     const u32x4 a = ga[m][bj]; float f[8] = {clampg(a.x << 16), clampg(a.x & 0xffff0000u), clampg(a.y << 16), clampg(a.y & 0xffff0000u), clampg(a.z << 16), clampg(a.z & 0xffff0000u), clampg(a.w << 16), clampg(a.w & 0xffff0000u)};
;                     if (br < 2) { const u32x4 b = gb[m][bj]; const float d[8] = {clampg(b.x << 16), clampg(b.x & 0xffff0000u), clampg(b.y << 16), clampg(b.y & 0xffff0000u), clampg(b.z << 16), clampg(b.z & 0xffff0000u), clampg(b.w << 16), clampg(b.w & 0xffff0000u)};
.LBB0_676:
	s_waitcnt vmcnt(6)
	v_lshlrev_b32_e32 v158, 16, v224
	v_max_u32_e32 v190, 0xda24260, v158
	v_and_b32_e32 v158, 0xffff0000, v224
	v_max_u32_e32 v191, 0xda24260, v158
	v_lshlrev_b32_e32 v158, 16, v225
	v_max_u32_e32 v160, 0xda24260, v158
	v_and_b32_e32 v158, 0xffff0000, v225
	v_max_u32_e32 v161, 0xda24260, v158
	v_lshlrev_b32_e32 v158, 16, v226
	v_max_u32_e32 v186, 0xda24260, v158
	v_and_b32_e32 v158, 0xffff0000, v226
	v_max_u32_e32 v187, 0xda24260, v158
	v_lshlrev_b32_e32 v158, 16, v227
	v_and_b32_e32 v159, 0xffff0000, v227
	v_max_u32_e32 v158, 0xda24260, v158
	v_max_u32_e32 v159, 0xda24260, v159
	s_and_b64 vcc, exec, s[6:7]
	s_mov_b64 s[2:3], -1
	s_cbranch_vccnz .LBB0_678
	s_mov_b64 s[2:3], 0

; __device__ __forceinline__ float clampg(unsigned bits) { return __uint_as_float(bits > 0x0da24260u ? bits : 0x0da24260u); }
;     __device__ __forceinline__ void operator()(acc_t& acc, const Unit& u, int wr, int wc, int fr, int fq) const {
;     ...
;             for (int m = 0; m < 4; ++m)
; #pragma unroll
;                 for (int bj = 0; bj < 2; ++bj) {
;                     const u32x4 a = ga[m][bj]; float f[8] = {clampg(a.x << 16), clampg(a.x & 0xffff0000u), clampg(a.y << 16), clampg(a.y & 0xffff0000u), clampg(a.z << 16), clampg(a.z & 0xffff0000u), clampg(a.w << 16), clampg(a.w & 0xffff0000u)};
;                     if (br < 2) { const u32x4 b = gb[m][bj]; const float d[8] = {clampg(b.x << 16), clampg(b.x & 0xffff0000u), clampg(b.y << 16), clampg(b.y & 0xffff0000u), clampg(b.z << 16), clampg(b.z & 0xffff0000u), clampg(b.w << 16), clampg(b.w & 0xffff0000u)};
.LBB0_683:
	s_waitcnt vmcnt(5)
	v_lshlrev_b32_e32 v154, 16, v228
	v_max_u32_e32 v158, 0xda24260, v154
	v_and_b32_e32 v154, 0xffff0000, v228
	v_max_u32_e32 v159, 0xda24260, v154
	v_lshlrev_b32_e32 v154, 16, v229
	v_max_u32_e32 v156, 0xda24260, v154
	v_and_b32_e32 v154, 0xffff0000, v229
	v_max_u32_e32 v157, 0xda24260, v154
	v_lshlrev_b32_e32 v154, 16, v230
	v_max_u32_e32 v160, 0xda24260, v154
	v_and_b32_e32 v154, 0xffff0000, v230
	v_max_u32_e32 v161, 0xda24260, v154
	v_lshlrev_b32_e32 v154, 16, v231
	v_and_b32_e32 v155, 0xffff0000, v231
	v_max_u32_e32 v154, 0xda24260, v154
	v_max_u32_e32 v155, 0xda24260, v155
	s_and_b64 vcc, exec, s[6:7]
	s_mov_b64 s[2:3], -1
	s_cbranch_vccnz .LBB0_685
	s_mov_b64 s[2:3], 0

; __device__ __forceinline__ float clampg(unsigned bits) { return __uint_as_float(bits > 0x0da24260u ? bits : 0x0da24260u); }
;     __device__ __forceinline__ void operator()(acc_t& acc, const Unit& u, int wr, int wc, int fr, int fq) const {
;     ...
;             for (int m = 0; m < 4; ++m)
; #pragma unroll
;                 for (int bj = 0; bj < 2; ++bj) {
;                     const u32x4 a = ga[m][bj]; float f[8] = {clampg(a.x << 16), clampg(a.x & 0xffff0000u), clampg(a.y << 16), clampg(a.y & 0xffff0000u), clampg(a.z << 16), clampg(a.z & 0xffff0000u), clampg(a.w << 16), clampg(a.w & 0xffff0000u)};
;                     if (br < 2) { const u32x4 b = gb[m][bj]; const float d[8] = {clampg(b.x << 16), clampg(b.x & 0xffff0000u), clampg(b.y << 16), clampg(b.y & 0xffff0000u), clampg(b.z << 16), clampg(b.z & 0xffff0000u), clampg(b.w << 16), clampg(b.w & 0xffff0000u)};
.LBB0_690:
	s_waitcnt vmcnt(4)
	v_lshlrev_b32_e32 v150, 16, v232
	v_max_u32_e32 v154, 0xda24260, v150
	v_and_b32_e32 v150, 0xffff0000, v232
	v_max_u32_e32 v155, 0xda24260, v150
	v_lshlrev_b32_e32 v150, 16, v233
	v_max_u32_e32 v152, 0xda24260, v150
	v_and_b32_e32 v150, 0xffff0000, v233
	v_max_u32_e32 v153, 0xda24260, v150
	v_lshlrev_b32_e32 v150, 16, v234
	v_max_u32_e32 v156, 0xda24260, v150
	v_and_b32_e32 v150, 0xffff0000, v234
	v_max_u32_e32 v157, 0xda24260, v150
	v_lshlrev_b32_e32 v150, 16, v235
	v_and_b32_e32 v151, 0xffff0000, v235
	v_max_u32_e32 v150, 0xda24260, v150
	v_max_u32_e32 v151, 0xda24260, v151
	s_and_b64 vcc, exec, s[6:7]
	s_mov_b64 s[2:3], -1
	s_cbranch_vccnz .LBB0_692
	s_mov_b64 s[2:3], 0

; __device__ __forceinline__ float clampg(unsigned bits) { return __uint_as_float(bits > 0x0da24260u ? bits : 0x0da24260u); }
;     __device__ __forceinline__ void operator()(acc_t& acc, const Unit& u, int wr, int wc, int fr, int fq) const {
;     ...
;             for (int m = 0; m < 4; ++m)
; #pragma unroll
;                 for (int bj = 0; bj < 2; ++bj) {
;                     const u32x4 a = ga[m][bj]; float f[8] = {clampg(a.x << 16), clampg(a.x & 0xffff0000u), clampg(a.y << 16), clampg(a.y & 0xffff0000u), clampg(a.z << 16), clampg(a.z & 0xffff0000u), clampg(a.w << 16), clampg(a.w & 0xffff0000u)};
;                     if (br < 2) { const u32x4 b = gb[m][bj]; const float d[8] = {clampg(b.x << 16), clampg(b.x & 0xffff0000u), clampg(b.y << 16), clampg(b.y & 0xffff0000u), clampg(b.z << 16), clampg(b.z & 0xffff0000u), clampg(b.w << 16), clampg(b.w & 0xffff0000u)};
.LBB0_697:
	s_waitcnt vmcnt(3)
	v_lshlrev_b32_e32 v146, 16, v236
	v_max_u32_e32 v150, 0xda24260, v146
	v_and_b32_e32 v146, 0xffff0000, v236
	v_max_u32_e32 v151, 0xda24260, v146
	v_lshlrev_b32_e32 v146, 16, v237
	v_max_u32_e32 v148, 0xda24260, v146
	v_and_b32_e32 v146, 0xffff0000, v237
	v_max_u32_e32 v149, 0xda24260, v146
	v_lshlrev_b32_e32 v146, 16, v238
	v_max_u32_e32 v152, 0xda24260, v146
	v_and_b32_e32 v146, 0xffff0000, v238
	v_max_u32_e32 v153, 0xda24260, v146
	v_lshlrev_b32_e32 v146, 16, v239
	v_and_b32_e32 v147, 0xffff0000, v239
	v_max_u32_e32 v146, 0xda24260, v146
	v_max_u32_e32 v147, 0xda24260, v147
	s_and_b64 vcc, exec, s[6:7]
	s_mov_b64 s[2:3], -1
	s_cbranch_vccnz .LBB0_699
	s_mov_b64 s[2:3], 0

; __device__ __forceinline__ float clampg(unsigned bits) { return __uint_as_float(bits > 0x0da24260u ? bits : 0x0da24260u); }
;     __device__ __forceinline__ void operator()(acc_t& acc, const Unit& u, int wr, int wc, int fr, int fq) const {
;     ...
;             for (int m = 0; m < 4; ++m)
; #pragma unroll
;                 for (int bj = 0; bj < 2; ++bj) {
;                     const u32x4 a = ga[m][bj]; float f[8] = {clampg(a.x << 16), clampg(a.x & 0xffff0000u), clampg(a.y << 16), clampg(a.y & 0xffff0000u), clampg(a.z << 16), clampg(a.z & 0xffff0000u), clampg(a.w << 16), clampg(a.w & 0xffff0000u)};
;                     if (br < 2) { const u32x4 b = gb[m][bj]; const float d[8] = {clampg(b.x << 16), clampg(b.x & 0xffff0000u), clampg(b.y << 16), clampg(b.y & 0xffff0000u), clampg(b.z << 16), clampg(b.z & 0xffff0000u), clampg(b.w << 16), clampg(b.w & 0xffff0000u)};
.LBB0_704:
	s_waitcnt vmcnt(2)
	v_lshlrev_b32_e32 v142, 16, v240
	v_max_u32_e32 v146, 0xda24260, v142
	v_and_b32_e32 v142, 0xffff0000, v240
	v_max_u32_e32 v147, 0xda24260, v142
	v_lshlrev_b32_e32 v142, 16, v241
	v_max_u32_e32 v144, 0xda24260, v142
	v_and_b32_e32 v142, 0xffff0000, v241
	v_max_u32_e32 v145, 0xda24260, v142
	v_lshlrev_b32_e32 v142, 16, v242
	v_max_u32_e32 v148, 0xda24260, v142
	v_and_b32_e32 v142, 0xffff0000, v242
	v_max_u32_e32 v149, 0xda24260, v142
	v_lshlrev_b32_e32 v142, 16, v243
	v_and_b32_e32 v143, 0xffff0000, v243
	v_max_u32_e32 v142, 0xda24260, v142
	v_max_u32_e32 v143, 0xda24260, v143
	s_and_b64 vcc, exec, s[6:7]
	s_mov_b64 s[2:3], -1
	s_cbranch_vccnz .LBB0_706
	s_mov_b64 s[2:3], 0
